# v029 + all validated wait relaxations: attention item prologue counted waits, tr-read vmcnt(0) removal, fix-unit scan batch single wait, LRU conv-stage store-ack waits dropped
# speedup vs baseline: 1.0099x; 1.0021x over previous
; #define LAS __attribute__((address_space(3)))
; template <int I> DI const float* kin() { return (const float*)karg64<I * 8>(); }
; DI float bflo(unsigned w) { return __uint_as_float(w << 16); }
; DI float bfhi(unsigned w) { return __uint_as_float(w & 0xffff0000u); }
; DI unsigned pk2(float a, float b) { f32x2 v = {a, b}; bf16v2 r = __builtin_convertvector(v, bf16v2); return __builtin_bit_cast(unsigned, r); }
; DI void lru_local_phase(const Ctx& c, int l) {
;     ...
; #pragma unroll
;         for (int hh = 0; hh < 2; ++hh) {
;             const int tt = tk + 32 * hh;
;             f32x4 a0 = *(const LAS f32x4*)(cwl + 512 + 8 * cg), a1 = *(const LAS f32x4*)(cwl + 512 + 8 * cg + 4);
; #pragma unroll
;             for (int k = 0; k < 4; ++k) {
;                 const int ts = tt - 3 + k;
;                 f32x4 x0, x1;
;                 if (ts >= 0 || (!smp && !first)) { const u32x4 v = pre[hh][k];
;                     x0 = (f32x4){bflo(v.x), bfhi(v.x), bflo(v.y), bfhi(v.y)}; x1 = (f32x4){bflo(v.z), bfhi(v.z), bflo(v.w), bfhi(v.w)};
;                 } else if (smp) {
;                     const float* sp = kin<2>() + (((size_t)l * 32 + bs) * 3 + (3 + ts)) * 1024 + ch0 + 8 * cg;
;                     x0 = *(const f32x4*)sp; x1 = *(const f32x4*)(sp + 4);
;                 } else { x0 = (f32x4){0.f, 0.f, 0.f, 0.f}; x1 = x0; }
;                 a0 += *(const LAS f32x4*)(cwl + k * 128 + 8 * cg) * x0; a1 += *(const LAS f32x4*)(cwl + k * 128 + 8 * cg + 4) * x1;
;             }
;             *(LAS f32x4*)(uf + tt * 132 + 8 * cg) = a0; *(LAS f32x4*)(uf + tt * 132 + 8 * cg + 4) = a1;
;             u32x4 pw; pw.x = pk2(a0[0], a0[1]); pw.y = pk2(a0[2], a0[3]); pw.z = pk2(a1[0], a1[1]); pw.w = pk2(a1[2], a1[3]);
;             *(LAS u32x4*)(ub + tt * 272 + 16 * cg) = pw;
;         }
.LBB0_366:
	s_ashr_i32 s4, s23, 3
	s_cmpk_gt_i32 s4, 0xff
	s_cselect_b64 s[8:9], -1, 0
	s_and_b32 s5, s23, 0x3f8
	s_cmp_eq_u32 s5, 0
	s_cselect_b64 s[64:65], -1, 0
	ds_read_b128 v[72:75], v141
	ds_read_b128 v[68:71], v141 offset:16
	s_add_i32 s12, s4, 0xffffff00
	s_or_b64 s[88:89], s[8:9], s[64:65]
	s_add_u32 s5, s86, s12
	s_addc_u32 s66, s87, 0
	s_and_b64 s[64:65], s[40:41], s[88:89]
	s_xor_b64 s[64:65], s[64:65], -1
	s_and_saveexec_b64 s[72:73], s[64:65]
	s_xor_b64 s[64:65], exec, s[72:73]
	s_cbranch_execz .LBB0_368
	s_waitcnt lgkmcnt(0)
	v_lshlrev_b32_e32 v76, 16, v4
	v_and_b32_e32 v77, 0xffff0000, v4
	v_lshlrev_b32_e32 v78, 16, v5
	v_and_b32_e32 v79, 0xffff0000, v5
	v_lshlrev_b32_e32 v80, 16, v6
	v_and_b32_e32 v81, 0xffff0000, v6
	v_lshlrev_b32_e32 v82, 16, v7
	v_and_b32_e32 v83, 0xffff0000, v7
.LBB0_368:
	s_or_saveexec_b64 s[94:95], s[64:65]
	s_mul_i32 s66, s66, 3
	s_mul_hi_u32 s64, s5, 3
	v_cndmask_b32_e64 v84, 0, 1, s[8:9]
	s_add_i32 s73, s64, s66
	s_mul_i32 s72, s5, 3
	v_cmp_ne_u32_e64 s[64:65], 1, v84
	s_xor_b64 exec, exec, s[94:95]
	s_cbranch_execz .LBB0_371
	v_mov_b32_e32 v79, 0
	s_and_b64 vcc, exec, s[64:65]
	v_mov_b32_e32 v78, 0
	v_mov_b32_e32 v77, 0
	v_mov_b32_e32 v76, 0
	v_mov_b32_e32 v83, 0
	v_mov_b32_e32 v82, 0
	v_mov_b32_e32 v81, 0
	v_mov_b32_e32 v80, 0
	s_cbranch_vccnz .LBB0_371
	v_lshl_add_u64 v[76:77], s[72:73], 0, v[134:135]
	s_load_dwordx2 s[66:67], s[0:1], 16
	s_waitcnt lgkmcnt(0)
	v_lshlrev_b64 v[76:77], 12, v[76:77]
	v_lshl_add_u64 v[76:77], s[66:67], 0, v[76:77]
	s_lshl_b32 s66, s26, 2
	s_mov_b32 s67, s13
	v_lshl_add_u64 v[76:77], v[76:77], 0, s[66:67]
	v_mov_b32_e32 v145, v3
	v_lshl_add_u64 v[80:81], v[76:77], 0, v[144:145]
	global_load_dwordx4 v[76:79], v[80:81], off
	s_nop 0
	global_load_dwordx4 v[80:83], v[80:81], off offset:16
	s_waitcnt vmcnt(0)
.LBB0_371:
	s_or_b64 exec, exec, s[94:95]
	ds_read_b128 v[88:91], v173
	ds_read_b128 v[84:87], v173 offset:16
	s_and_b64 s[66:67], s[42:43], s[88:89]
	s_xor_b64 s[66:67], s[66:67], -1
	s_and_saveexec_b64 s[78:79], s[66:67]
	s_xor_b64 s[94:95], exec, s[78:79]
	s_cbranch_execz .LBB0_373
	s_waitcnt lgkmcnt(0)
	v_lshlrev_b32_e32 v92, 16, v8
	v_and_b32_e32 v93, 0xffff0000, v8
	v_lshlrev_b32_e32 v94, 16, v9
	v_and_b32_e32 v95, 0xffff0000, v9
	v_lshlrev_b32_e32 v96, 16, v10
	v_and_b32_e32 v97, 0xffff0000, v10
	v_lshlrev_b32_e32 v98, 16, v11
	v_and_b32_e32 v99, 0xffff0000, v11
.LBB0_373:
	s_andn2_saveexec_b64 s[94:95], s[94:95]
	s_cbranch_execz .LBB0_376
	v_mov_b32_e32 v95, 0
	s_and_b64 vcc, exec, s[64:65]
	v_mov_b32_e32 v94, 0
	v_mov_b32_e32 v93, 0
	v_mov_b32_e32 v92, 0
	v_mov_b32_e32 v99, 0
	v_mov_b32_e32 v98, 0
	v_mov_b32_e32 v97, 0
	v_mov_b32_e32 v96, 0
	s_cbranch_vccnz .LBB0_376
	v_lshl_add_u64 v[92:93], s[72:73], 0, v[146:147]
	s_load_dwordx2 s[66:67], s[0:1], 16
	s_waitcnt lgkmcnt(0)
	v_lshlrev_b64 v[92:93], 12, v[92:93]
	v_lshl_add_u64 v[92:93], s[66:67], 0, v[92:93]
	s_lshl_b32 s66, s26, 2
	s_mov_b32 s67, s13
	v_lshl_add_u64 v[92:93], v[92:93], 0, s[66:67]
	v_mov_b32_e32 v145, v3
	v_lshl_add_u64 v[96:97], v[92:93], 0, v[144:145]
	global_load_dwordx4 v[92:95], v[96:97], off
	s_nop 0
	global_load_dwordx4 v[96:99], v[96:97], off offset:16
	s_waitcnt vmcnt(0)
.LBB0_376:
	s_or_b64 exec, exec, s[94:95]
	ds_read_b128 v[108:111], v173 offset:512
	ds_read_b128 v[100:103], v173 offset:528
	s_and_b64 s[66:67], s[44:45], s[88:89]
	s_xor_b64 s[66:67], s[66:67], -1
	s_and_saveexec_b64 s[78:79], s[66:67]
	s_xor_b64 s[94:95], exec, s[78:79]
	s_cbranch_execz .LBB0_378
	s_waitcnt lgkmcnt(0)
	v_lshlrev_b32_e32 v104, 16, v12
	v_and_b32_e32 v105, 0xffff0000, v12
	v_lshlrev_b32_e32 v106, 16, v13
	v_and_b32_e32 v107, 0xffff0000, v13
	v_lshlrev_b32_e32 v112, 16, v14
	v_and_b32_e32 v113, 0xffff0000, v14
	v_lshlrev_b32_e32 v114, 16, v15
	v_and_b32_e32 v115, 0xffff0000, v15
.LBB0_378:
	s_andn2_saveexec_b64 s[94:95], s[94:95]
	s_cbranch_execz .LBB0_381
	v_mov_b32_e32 v107, 0
	s_and_b64 vcc, exec, s[64:65]
	v_mov_b32_e32 v106, 0
	v_mov_b32_e32 v105, 0
	v_mov_b32_e32 v104, 0
	v_mov_b32_e32 v115, 0
	v_mov_b32_e32 v114, 0
	v_mov_b32_e32 v113, 0
	v_mov_b32_e32 v112, 0
	s_cbranch_vccnz .LBB0_381
	v_lshl_add_u64 v[104:105], s[72:73], 0, v[148:149]
	s_load_dwordx2 s[66:67], s[0:1], 16
	s_waitcnt lgkmcnt(0)
	v_lshlrev_b64 v[104:105], 12, v[104:105]
	v_lshl_add_u64 v[104:105], s[66:67], 0, v[104:105]
	s_lshl_b32 s66, s26, 2
	s_mov_b32 s67, s13
	v_lshl_add_u64 v[104:105], v[104:105], 0, s[66:67]
	v_mov_b32_e32 v145, v3
	v_lshl_add_u64 v[112:113], v[104:105], 0, v[144:145]
	global_load_dwordx4 v[104:107], v[112:113], off
	s_nop 0
	global_load_dwordx4 v[112:115], v[112:113], off offset:16
	s_waitcnt vmcnt(0)
.LBB0_381:
	s_or_b64 exec, exec, s[94:95]
	ds_read_b128 v[120:123], v173 offset:1024
	ds_read_b128 v[116:119], v173 offset:1040
	s_and_b64 s[66:67], s[46:47], s[88:89]
	s_xor_b64 s[66:67], s[66:67], -1
	s_and_saveexec_b64 s[78:79], s[66:67]
	s_xor_b64 s[94:95], exec, s[78:79]
	s_cbranch_execz .LBB0_383
	s_waitcnt lgkmcnt(0)
	v_lshlrev_b32_e32 v124, 16, v16
	v_and_b32_e32 v125, 0xffff0000, v16
	v_lshlrev_b32_e32 v126, 16, v17
	v_and_b32_e32 v127, 0xffff0000, v17
	v_lshlrev_b32_e32 v128, 16, v18
	v_and_b32_e32 v129, 0xffff0000, v18
	v_lshlrev_b32_e32 v130, 16, v19
	v_and_b32_e32 v131, 0xffff0000, v19
; #define LAS __attribute__((address_space(3)))
; template <int I> DI const float* kin() { return (const float*)karg64<I * 8>(); }
; DI float bflo(unsigned w) { return __uint_as_float(w << 16); }
; DI float bfhi(unsigned w) { return __uint_as_float(w & 0xffff0000u); }
; DI unsigned pk2(float a, float b) { f32x2 v = {a, b}; bf16v2 r = __builtin_convertvector(v, bf16v2); return __builtin_bit_cast(unsigned, r); }
; DI void lru_local_phase(const Ctx& c, int l) {
;     ...
; #pragma unroll
;         for (int hh = 0; hh < 2; ++hh) {
;             const int tt = tk + 32 * hh;
;             f32x4 a0 = *(const LAS f32x4*)(cwl + 512 + 8 * cg), a1 = *(const LAS f32x4*)(cwl + 512 + 8 * cg + 4);
; #pragma unroll
;             for (int k = 0; k < 4; ++k) {
;                 const int ts = tt - 3 + k;
;                 f32x4 x0, x1;
;                 if (ts >= 0 || (!smp && !first)) { const u32x4 v = pre[hh][k];
;                     x0 = (f32x4){bflo(v.x), bfhi(v.x), bflo(v.y), bfhi(v.y)}; x1 = (f32x4){bflo(v.z), bfhi(v.z), bflo(v.w), bfhi(v.w)};
;                 } else if (smp) {
;                     const float* sp = kin<2>() + (((size_t)l * 32 + bs) * 3 + (3 + ts)) * 1024 + ch0 + 8 * cg;
;                     x0 = *(const f32x4*)sp; x1 = *(const f32x4*)(sp + 4);
;                 } else { x0 = (f32x4){0.f, 0.f, 0.f, 0.f}; x1 = x0; }
;                 a0 += *(const LAS f32x4*)(cwl + k * 128 + 8 * cg) * x0; a1 += *(const LAS f32x4*)(cwl + k * 128 + 8 * cg + 4) * x1;
;             }
;             *(LAS f32x4*)(uf + tt * 132 + 8 * cg) = a0; *(LAS f32x4*)(uf + tt * 132 + 8 * cg + 4) = a1;
;             u32x4 pw; pw.x = pk2(a0[0], a0[1]); pw.y = pk2(a0[2], a0[3]); pw.z = pk2(a1[0], a1[1]); pw.w = pk2(a1[2], a1[3]);
;             *(LAS u32x4*)(ub + tt * 272 + 16 * cg) = pw;
;         }
.LBB0_383:
	s_andn2_saveexec_b64 s[94:95], s[94:95]
	s_cbranch_execz .LBB0_386
	v_mov_b32_e32 v127, 0
	s_and_b64 vcc, exec, s[64:65]
	v_mov_b32_e32 v126, 0
	v_mov_b32_e32 v125, 0
	v_mov_b32_e32 v124, 0
	v_mov_b32_e32 v131, 0
	v_mov_b32_e32 v130, 0
	v_mov_b32_e32 v129, 0
	v_mov_b32_e32 v128, 0
	s_cbranch_vccnz .LBB0_386
	v_lshl_add_u64 v[124:125], s[72:73], 0, v[150:151]
	s_load_dwordx2 s[66:67], s[0:1], 16
	s_waitcnt lgkmcnt(0)
	v_lshlrev_b64 v[124:125], 12, v[124:125]
	v_lshl_add_u64 v[124:125], s[66:67], 0, v[124:125]
	s_lshl_b32 s66, s26, 2
	s_mov_b32 s67, s13
	v_lshl_add_u64 v[124:125], v[124:125], 0, s[66:67]
	v_mov_b32_e32 v145, v3
	v_lshl_add_u64 v[128:129], v[124:125], 0, v[144:145]
	global_load_dwordx4 v[124:127], v[128:129], off
	s_nop 0
	global_load_dwordx4 v[128:131], v[128:129], off offset:16
	s_waitcnt vmcnt(0)
.LBB0_386:
	s_or_b64 exec, exec, s[94:95]
	s_waitcnt lgkmcnt(0)
	v_pk_fma_f32 v[74:75], v[78:79], v[90:91], v[74:75]
	v_pk_fma_f32 v[72:73], v[76:77], v[88:89], v[72:73]
	v_pk_fma_f32 v[70:71], v[82:83], v[86:87], v[70:71]
	v_pk_fma_f32 v[68:69], v[80:81], v[84:85], v[68:69]
	v_pk_fma_f32 v[74:75], v[94:95], v[110:111], v[74:75]
	v_pk_fma_f32 v[72:73], v[92:93], v[108:109], v[72:73]
	v_pk_fma_f32 v[76:77], v[98:99], v[102:103], v[70:71]
	v_pk_fma_f32 v[78:79], v[96:97], v[100:101], v[68:69]
	v_pk_fma_f32 v[80:81], v[106:107], v[122:123], v[74:75]
	ds_read_b128 v[68:71], v173 offset:1536
	v_pk_fma_f32 v[82:83], v[104:105], v[120:121], v[72:73]
	ds_read_b128 v[72:75], v173 offset:1552
	v_pk_fma_f32 v[76:77], v[114:115], v[118:119], v[76:77]
	v_pk_fma_f32 v[78:79], v[112:113], v[116:117], v[78:79]
	s_waitcnt lgkmcnt(1)
	v_pk_fma_f32 v[70:71], v[126:127], v[70:71], v[80:81]
	v_pk_fma_f32 v[68:69], v[124:125], v[68:69], v[82:83]
	s_waitcnt lgkmcnt(0)
	v_pk_fma_f32 v[74:75], v[130:131], v[74:75], v[76:77]
	v_pk_fma_f32 v[72:73], v[128:129], v[72:73], v[78:79]
	ds_write_b128 v233, v[68:71]
	ds_write_b128 v233, v[72:75] offset:16
	v_cvt_pk_bf16_f32 v68, v68, v69
	v_cvt_pk_bf16_f32 v69, v70, v71
	v_cvt_pk_bf16_f32 v70, v72, v73
	v_cvt_pk_bf16_f32 v71, v74, v75
	ds_write_b128 v234, v[68:71] offset:33792
	ds_read_b128 v[72:75], v141
	ds_read_b128 v[68:71], v141 offset:16
	s_and_b64 s[66:67], s[48:49], s[88:89]
	s_xor_b64 s[66:67], s[66:67], -1
	s_and_saveexec_b64 s[78:79], s[66:67]
	s_xor_b64 s[94:95], exec, s[78:79]
	v_lshlrev_b32_e32 v76, 16, v20
	v_and_b32_e32 v77, 0xffff0000, v20
	v_lshlrev_b32_e32 v78, 16, v21
	v_and_b32_e32 v79, 0xffff0000, v21
	v_lshlrev_b32_e32 v80, 16, v22
	v_and_b32_e32 v81, 0xffff0000, v22
	v_lshlrev_b32_e32 v82, 16, v23
	v_and_b32_e32 v83, 0xffff0000, v23
	s_andn2_saveexec_b64 s[94:95], s[94:95]
	s_cbranch_execz .LBB0_391
	v_mov_b32_e32 v79, 0
	s_and_b64 vcc, exec, s[64:65]
	v_mov_b32_e32 v78, 0
	v_mov_b32_e32 v77, 0
	v_mov_b32_e32 v76, 0
	v_mov_b32_e32 v83, 0
	v_mov_b32_e32 v82, 0
	v_mov_b32_e32 v81, 0
	v_mov_b32_e32 v80, 0
	s_cbranch_vccnz .LBB0_391
	v_lshl_add_u64 v[76:77], s[72:73], 0, v[136:137]
	s_load_dwordx2 s[66:67], s[0:1], 16
	s_waitcnt lgkmcnt(0)
	v_lshlrev_b64 v[76:77], 12, v[76:77]
	v_lshl_add_u64 v[76:77], s[66:67], 0, v[76:77]
	s_lshl_b32 s66, s26, 2
	s_mov_b32 s67, s13
	v_lshl_add_u64 v[76:77], v[76:77], 0, s[66:67]
	v_mov_b32_e32 v145, v3
	v_lshl_add_u64 v[80:81], v[76:77], 0, v[144:145]
	global_load_dwordx4 v[76:79], v[80:81], off
	s_nop 0
	global_load_dwordx4 v[80:83], v[80:81], off offset:16
	s_waitcnt vmcnt(0)
.LBB0_391:
	s_or_b64 exec, exec, s[94:95]
	ds_read_b128 v[88:91], v173
	ds_read_b128 v[84:87], v173 offset:16
	s_and_b64 s[66:67], s[50:51], s[88:89]
	s_xor_b64 s[66:67], s[66:67], -1
	s_and_saveexec_b64 s[78:79], s[66:67]
	s_xor_b64 s[94:95], exec, s[78:79]
	v_lshlrev_b32_e32 v92, 16, v24
	v_and_b32_e32 v93, 0xffff0000, v24
	v_lshlrev_b32_e32 v94, 16, v25
	v_and_b32_e32 v95, 0xffff0000, v25
	v_lshlrev_b32_e32 v96, 16, v26
	v_and_b32_e32 v97, 0xffff0000, v26
	v_lshlrev_b32_e32 v98, 16, v27
	v_and_b32_e32 v99, 0xffff0000, v27
	s_andn2_saveexec_b64 s[94:95], s[94:95]
	s_cbranch_execz .LBB0_396
	v_mov_b32_e32 v95, 0
	s_and_b64 vcc, exec, s[64:65]
	v_mov_b32_e32 v94, 0
	v_mov_b32_e32 v93, 0
	v_mov_b32_e32 v92, 0
	v_mov_b32_e32 v99, 0
	v_mov_b32_e32 v98, 0
	v_mov_b32_e32 v97, 0
	v_mov_b32_e32 v96, 0
	s_cbranch_vccnz .LBB0_396
	v_lshl_add_u64 v[92:93], s[72:73], 0, v[152:153]
	s_load_dwordx2 s[66:67], s[0:1], 16
	s_waitcnt lgkmcnt(0)
	v_lshlrev_b64 v[92:93], 12, v[92:93]
	v_lshl_add_u64 v[92:93], s[66:67], 0, v[92:93]
	s_lshl_b32 s66, s26, 2
	s_mov_b32 s67, s13
	v_lshl_add_u64 v[92:93], v[92:93], 0, s[66:67]
	v_mov_b32_e32 v145, v3
	v_lshl_add_u64 v[96:97], v[92:93], 0, v[144:145]
	global_load_dwordx4 v[92:95], v[96:97], off
	s_nop 0
	global_load_dwordx4 v[96:99], v[96:97], off offset:16
	s_waitcnt vmcnt(0)
; #define LAS __attribute__((address_space(3)))
; template <int I> DI const float* kin() { return (const float*)karg64<I * 8>(); }
; DI float bflo(unsigned w) { return __uint_as_float(w << 16); }
; DI float bfhi(unsigned w) { return __uint_as_float(w & 0xffff0000u); }
; DI unsigned pk2(float a, float b) { f32x2 v = {a, b}; bf16v2 r = __builtin_convertvector(v, bf16v2); return __builtin_bit_cast(unsigned, r); }
; DI void lru_local_phase(const Ctx& c, int l) {
;     ...
; #pragma unroll
;         for (int hh = 0; hh < 2; ++hh) {
;             const int tt = tk + 32 * hh;
;             f32x4 a0 = *(const LAS f32x4*)(cwl + 512 + 8 * cg), a1 = *(const LAS f32x4*)(cwl + 512 + 8 * cg + 4);
; #pragma unroll
;             for (int k = 0; k < 4; ++k) {
;                 const int ts = tt - 3 + k;
;                 f32x4 x0, x1;
;                 if (ts >= 0 || (!smp && !first)) { const u32x4 v = pre[hh][k];
;                     x0 = (f32x4){bflo(v.x), bfhi(v.x), bflo(v.y), bfhi(v.y)}; x1 = (f32x4){bflo(v.z), bfhi(v.z), bflo(v.w), bfhi(v.w)};
;                 } else if (smp) {
;                     const float* sp = kin<2>() + (((size_t)l * 32 + bs) * 3 + (3 + ts)) * 1024 + ch0 + 8 * cg;
;                     x0 = *(const f32x4*)sp; x1 = *(const f32x4*)(sp + 4);
;                 } else { x0 = (f32x4){0.f, 0.f, 0.f, 0.f}; x1 = x0; }
;                 a0 += *(const LAS f32x4*)(cwl + k * 128 + 8 * cg) * x0; a1 += *(const LAS f32x4*)(cwl + k * 128 + 8 * cg + 4) * x1;
;             }
;             *(LAS f32x4*)(uf + tt * 132 + 8 * cg) = a0; *(LAS f32x4*)(uf + tt * 132 + 8 * cg + 4) = a1;
;             u32x4 pw; pw.x = pk2(a0[0], a0[1]); pw.y = pk2(a0[2], a0[3]); pw.z = pk2(a1[0], a1[1]); pw.w = pk2(a1[2], a1[3]);
;             *(LAS u32x4*)(ub + tt * 272 + 16 * cg) = pw;
;         }
;         if (u + c.G < nunits) LRU_PREFETCH(u + c.G);
.LBB0_396:
	s_or_b64 exec, exec, s[94:95]
	ds_read_b128 v[108:111], v173 offset:512
	ds_read_b128 v[100:103], v173 offset:528
	s_and_b64 s[66:67], s[52:53], s[88:89]
	s_xor_b64 s[66:67], s[66:67], -1
	s_and_saveexec_b64 s[78:79], s[66:67]
	s_xor_b64 s[94:95], exec, s[78:79]
	v_lshlrev_b32_e32 v104, 16, v28
	v_and_b32_e32 v105, 0xffff0000, v28
	v_lshlrev_b32_e32 v106, 16, v29
	v_and_b32_e32 v107, 0xffff0000, v29
	v_lshlrev_b32_e32 v112, 16, v30
	v_and_b32_e32 v113, 0xffff0000, v30
	v_lshlrev_b32_e32 v114, 16, v31
	v_and_b32_e32 v115, 0xffff0000, v31
	s_andn2_saveexec_b64 s[94:95], s[94:95]
	s_cbranch_execz .LBB0_401
	v_mov_b32_e32 v107, 0
	s_and_b64 vcc, exec, s[64:65]
	v_mov_b32_e32 v106, 0
	v_mov_b32_e32 v105, 0
	v_mov_b32_e32 v104, 0
	v_mov_b32_e32 v115, 0
	v_mov_b32_e32 v114, 0
	v_mov_b32_e32 v113, 0
	v_mov_b32_e32 v112, 0
	s_cbranch_vccnz .LBB0_401
	v_lshl_add_u64 v[104:105], s[72:73], 0, v[154:155]
	s_load_dwordx2 s[66:67], s[0:1], 16
	s_waitcnt lgkmcnt(0)
	v_lshlrev_b64 v[104:105], 12, v[104:105]
	v_lshl_add_u64 v[104:105], s[66:67], 0, v[104:105]
	s_lshl_b32 s66, s26, 2
	s_mov_b32 s67, s13
	v_lshl_add_u64 v[104:105], v[104:105], 0, s[66:67]
	v_mov_b32_e32 v145, v3
	v_lshl_add_u64 v[112:113], v[104:105], 0, v[144:145]
	global_load_dwordx4 v[104:107], v[112:113], off
	s_nop 0
	global_load_dwordx4 v[112:115], v[112:113], off offset:16
	s_waitcnt vmcnt(0)
.LBB0_401:
	s_or_b64 exec, exec, s[94:95]
	ds_read_b128 v[120:123], v173 offset:1024
	ds_read_b128 v[116:119], v173 offset:1040
	s_and_b64 s[66:67], s[54:55], s[88:89]
	s_xor_b64 s[66:67], s[66:67], -1
	s_and_saveexec_b64 s[78:79], s[66:67]
	s_xor_b64 s[88:89], exec, s[78:79]
	v_lshlrev_b32_e32 v124, 16, v32
	v_and_b32_e32 v125, 0xffff0000, v32
	v_lshlrev_b32_e32 v126, 16, v33
	v_and_b32_e32 v127, 0xffff0000, v33
	v_lshlrev_b32_e32 v128, 16, v34
	v_and_b32_e32 v129, 0xffff0000, v34
	v_lshlrev_b32_e32 v130, 16, v35
	v_and_b32_e32 v131, 0xffff0000, v35
	s_andn2_saveexec_b64 s[88:89], s[88:89]
	s_cbranch_execz .LBB0_406
	v_mov_b32_e32 v127, 0
	s_and_b64 vcc, exec, s[64:65]
	v_mov_b32_e32 v126, 0
	v_mov_b32_e32 v125, 0
	v_mov_b32_e32 v124, 0
	v_mov_b32_e32 v131, 0
	v_mov_b32_e32 v130, 0
	v_mov_b32_e32 v129, 0
	v_mov_b32_e32 v128, 0
	s_cbranch_vccnz .LBB0_406
	v_lshl_add_u64 v[124:125], s[72:73], 0, v[156:157]
	s_load_dwordx2 s[64:65], s[0:1], 16
	s_waitcnt lgkmcnt(0)
	v_lshlrev_b64 v[124:125], 12, v[124:125]
	v_lshl_add_u64 v[124:125], s[64:65], 0, v[124:125]
	s_lshl_b32 s64, s26, 2
	s_mov_b32 s65, s13
	v_lshl_add_u64 v[124:125], v[124:125], 0, s[64:65]
	v_mov_b32_e32 v145, v3
	v_lshl_add_u64 v[128:129], v[124:125], 0, v[144:145]
	global_load_dwordx4 v[124:127], v[128:129], off
	s_nop 0
	global_load_dwordx4 v[128:131], v[128:129], off offset:16
	s_waitcnt vmcnt(0)
.LBB0_406:
	s_or_b64 exec, exec, s[88:89]
	s_waitcnt lgkmcnt(0)
	v_pk_fma_f32 v[74:75], v[78:79], v[90:91], v[74:75]
	v_pk_fma_f32 v[72:73], v[76:77], v[88:89], v[72:73]
	v_pk_fma_f32 v[70:71], v[82:83], v[86:87], v[70:71]
	v_pk_fma_f32 v[68:69], v[80:81], v[84:85], v[68:69]
	v_pk_fma_f32 v[74:75], v[94:95], v[110:111], v[74:75]
	v_pk_fma_f32 v[72:73], v[92:93], v[108:109], v[72:73]
	v_pk_fma_f32 v[76:77], v[98:99], v[102:103], v[70:71]
	v_pk_fma_f32 v[78:79], v[96:97], v[100:101], v[68:69]
	v_pk_fma_f32 v[80:81], v[106:107], v[122:123], v[74:75]
	ds_read_b128 v[68:71], v173 offset:1536
	v_pk_fma_f32 v[82:83], v[104:105], v[120:121], v[72:73]
	ds_read_b128 v[72:75], v173 offset:1552
	s_add_i32 s23, s23, s81
	v_pk_fma_f32 v[76:77], v[114:115], v[118:119], v[76:77]
	v_pk_fma_f32 v[78:79], v[112:113], v[116:117], v[78:79]
	s_cmpk_gt_i32 s23, 0x8ff
	s_waitcnt lgkmcnt(1)
	v_pk_fma_f32 v[70:71], v[126:127], v[70:71], v[80:81]
	v_pk_fma_f32 v[68:69], v[124:125], v[68:69], v[82:83]
	s_waitcnt lgkmcnt(0)
	v_pk_fma_f32 v[74:75], v[130:131], v[74:75], v[76:77]
	v_pk_fma_f32 v[72:73], v[128:129], v[72:73], v[78:79]
	s_cselect_b64 s[64:65], -1, 0
	ds_write_b128 v233, v[68:71] offset:16896
	ds_write_b128 v233, v[72:75] offset:16912
	v_cvt_pk_bf16_f32 v68, v68, v69
	v_cvt_pk_bf16_f32 v69, v70, v71
	v_cvt_pk_bf16_f32 v70, v72, v73
	v_cvt_pk_bf16_f32 v71, v74, v75
	s_and_b64 vcc, exec, s[64:65]
	ds_write_b128 v234, v[68:71] offset:42496
	s_cbranch_vccnz .LBB0_424
	s_ashr_i32 s5, s23, 3
	s_cmpk_gt_i32 s5, 0xff
	s_cselect_b64 s[66:67], -1, 0
	s_and_b32 s71, s23, 0x3f8
	s_cmp_eq_u32 s71, 0
	s_cselect_b64 s[72:73], -1, 0
	s_or_b64 s[72:73], s[66:67], s[72:73]
	s_lshl_b32 s66, s23, 8
	s_and_b32 s66, s66, 0x700
	s_mov_b32 s67, s13
	v_lshl_add_u64 v[68:69], v[158:159], 0, s[66:67]
	s_and_b64 s[66:67], s[40:41], s[72:73]
	s_lshl_b32 s5, s5, 6
	s_xor_b64 s[66:67], s[66:67], -1
	s_and_saveexec_b64 s[88:89], s[66:67]
	s_cbranch_execz .LBB0_409
	v_add_u32_e32 v4, s5, v139
	v_mad_i64_i32 v[4:5], s[66:67], v4, s31, v[68:69]
	global_load_dwordx4 v[4:7], v[4:5], off

; #define LAS __attribute__((address_space(3)))
; template <int I> DI const float* kin() { return (const float*)karg64<I * 8>(); }
; #define WSP(T, off) ((T*)(kws() + (off)))
; #define REP(j) for (int rep_ = 0; rep_ < 1 + ((PROBE_MASK >> (j)) & 1); ++rep_)
; template <int MODE, class Src>
; DI void attn_item(LAS unsigned char* lds, const Src& src, const bf16_t* Qp  , bf16_t* Op  , int nband, int jj0, float sink_l2, const LAS float* tbl, int qbase, int tid) {
;     ...
;     bf16x8 qf[8];
; #pragma unroll
;     for (int ks = 0; ks < 8; ++ks) qf[ks] = *(const bf16x8*)(Qp + (size_t)r * ZLD + ks * 16 + h * 8);
;     f32x16 o[4];
; #pragma unroll
;     for (int db = 0; db < 4; ++db)
; #pragma unroll
;         for (int i = 0; i < 16; ++i) o[db][i] = 0.f;
;     float mrun = MODE == 0 ? sink_l2 : -1e30f, lrun = MODE == 0 ? 1.f : 0.f;
;     const float sc = 0.08838834764831845f * LOG2E;
;     const LAS unsigned char* Kt = lds + hl * 16384 + 256 * r;
;     const int kx = 16 * (h ^ (((r & 3) << 2) | ((r >> 2) & 3)));
;     const int blk = (lane >> 4) & 1, q = (lane & 15) >> 2, p = lane & 3;
;     const LAS unsigned char* Vt = lds + 65536 + hl * 16384 + 256 * (4 * h + q) + 8 * (p & 1);
;     const int vlo = 2 * blk + (p >> 1);
;     ATT_ISSUE(jj0, false); ATT_ISSUE(jj0, true);
; __global__ void __launch_bounds__(NTHR, 2) fwd_kernel(Args args) {
;     ...
;             REP(13) for (int u = c.bid; u < (c.G >= 128 ? 512 : NCHUNK * 2); u += c.G) {
;                 const int chunk = u >> 1, kv = u & 1, head = kv * 4 + (c.wave >> 1), qh = c.wave & 1;
;                 const bf16_t* Z = WSP(bf16_t, WS_Z);
;                 SrcSwa src{Z, WSP(bf16_t, WS_KCB), WSP(bf16_t, WS_VTCB), chunk, kv};
;                 const int n = chunk & 127, jj0 = (chunk < 256 && n < 2) ? 2 - n : 0;
;                 attn_item<0>(c.lds, src, Z + (size_t)(chunk * 64 + qh * 32) * ZLD + C_QB + head * 128, WSP(bf16_t, WS_BR) + (size_t)(chunk * 64 + qh * 32) * 3072 + 1024 + head * 128, 3, jj0,
;                              kin<17>()[l * 8 + head] * LOG2E, nullptr, 0, c.tid);
.LBB0_474:
	v_lshlrev_b32_e32 v5, 3, v6
	s_add_u32 s34, s34, s60
	v_mul_lo_u32 v8, s39, v142
	v_mul_lo_u32 v9, s38, v133
	v_mad_u64_u32 v[6:7], s[38:39], s38, v142, 0
	s_addc_u32 s35, s35, 0
	v_add3_u32 v7, v7, v9, v8
	v_lshl_add_u64 v[6:7], v[6:7], 1, s[34:35]
	v_lshlrev_b32_e32 v144, 1, v5
	v_mov_b32_e32 v145, v3
	s_add_i32 s63, s61, 0x10000
	v_lshl_add_u64 v[6:7], v[6:7], 0, v[144:145]
	s_mov_b32 m0, s63
	s_add_u32 s38, s53, s66
	global_load_lds_dwordx4 v[6:7], off
	s_addc_u32 s39, s54, s64
	s_add_u32 s34, s38, 0x1800
	s_addc_u32 s35, s39, 0
	s_lshl_b32 s42, s52, 7
	s_add_u32 s38, s38, 0x1a00
	s_addc_u32 s39, s39, 0
	s_add_i32 s64, s55, -1
	s_add_i32 s42, s42, s65
	s_add_i32 s44, s42, 0xffff8040
	s_add_i32 s42, s64, s52
	s_mul_hi_i32 s43, s42, 0xd0000
	s_mul_i32 s42, s42, 0xd0000
	s_add_u32 s42, s46, s42
	s_addc_u32 s43, s47, s43
	v_mov_b32_e32 v18, v3
	v_mov_b32_e32 v19, v3
	s_waitcnt vmcnt(4) lgkmcnt(0)
	v_mul_f32_e32 v137, 0x3fb8aa3b, v4
	s_add_u32 s46, s42, 0x26457a00
	v_mov_b32_e32 v4, v3
	v_mov_b32_e32 v5, v3
	v_mov_b32_e32 v6, v3
	v_mov_b32_e32 v7, v3
	v_mov_b32_e32 v8, v3
	v_mov_b32_e32 v9, v3
	v_mov_b32_e32 v10, v3
	v_mov_b32_e32 v11, v3
	v_mov_b32_e32 v12, v3
	v_mov_b32_e32 v13, v3
	v_mov_b32_e32 v14, v3
	v_mov_b32_e32 v15, v3
	v_mov_b32_e32 v16, v3
	v_mov_b32_e32 v17, v3
	v_mov_b64_e32 v[34:35], v[18:19]
	v_mov_b64_e32 v[50:51], v[18:19]
	v_mov_b64_e32 v[66:67], v[18:19]
	s_addc_u32 s47, s43, 0
	v_mov_b32_e32 v135, 1.0
	v_mov_b64_e32 v[32:33], v[16:17]
	v_mov_b64_e32 v[30:31], v[14:15]
	v_mov_b64_e32 v[28:29], v[12:13]
	v_mov_b64_e32 v[26:27], v[10:11]
	v_mov_b64_e32 v[24:25], v[8:9]
	v_mov_b64_e32 v[22:23], v[6:7]
	v_mov_b64_e32 v[20:21], v[4:5]
	v_mov_b64_e32 v[48:49], v[16:17]
	v_mov_b64_e32 v[46:47], v[14:15]
	v_mov_b64_e32 v[44:45], v[12:13]
	v_mov_b64_e32 v[42:43], v[10:11]
	v_mov_b64_e32 v[40:41], v[8:9]
	v_mov_b64_e32 v[38:39], v[6:7]
	v_mov_b64_e32 v[36:37], v[4:5]
	v_mov_b64_e32 v[64:65], v[16:17]
	v_mov_b64_e32 v[62:63], v[14:15]
	v_mov_b64_e32 v[60:61], v[12:13]
	v_mov_b64_e32 v[58:59], v[10:11]
	v_mov_b64_e32 v[56:57], v[8:9]
	v_mov_b64_e32 v[54:55], v[6:7]
	v_mov_b64_e32 v[52:53], v[4:5]
	s_branch .LBB0_477

; DI void attn_quad(LAS unsigned char* lds, const bf16_t* Z, bf16_t* BR, int c0  , int head, const LAS float* tbl, int tid) {
;     ...
;     const int n0 = c0 & 127, j0 = n0 < 8 ? 8 - n0 : 0;
;     const bf16_t* Qp = Z + (size_t)((c0 + qc) * 64 + qh * 32) * ZLD + C_QC + head * 128;
;     bf16_t* Op = BR + (size_t)((c0 + qc) * 64 + qh * 32) * 3072 + 2048 + head * 128;
;     ...
;     bf16x8 qf[8];
; #pragma unroll
;     for (int ks = 0; ks < 8; ++ks) qf[ks] = *(const bf16x8*)(Qp + (size_t)r * ZLD + ks * 16 + h * 8);
;     f32x16 o[4];
; #pragma unroll
;     for (int db = 0; db < 4; ++db)
; #pragma unroll
;         for (int i = 0; i < 16; ++i) o[db][i] = 0.f;
;     float mrun = -1e30f, lrun = 0.f;
;     const float sc = 0.08838834764831845f * LOG2E;
;     const int kx = 16 * (h ^ (((r & 3) << 2) | ((r >> 2) & 3)));
;     const int blk = (lane >> 4) & 1, q = (lane & 15) >> 2, p = lane & 3;
;     const int vlo = 2 * blk + (p >> 1);
;     const int qbase = qh * 32;
;     AQ_ISSUE(j0); if (j0 + 1 < 12) AQ_ISSUE(j0 + 1); if (j0 + 2 < 12) AQ_ISSUE(j0 + 2);
.LBB0_563:
	s_and_b32 s4, s34, 7
	s_mul_i32 s10, s4, 0x410
	s_ashr_i32 s5, s34, 1
	s_add_i32 s22, s10, 0
	v_readfirstlane_b32 s10, v146
	s_and_b32 s26, s5, -4
	s_ashr_i32 s35, s10, 6
	s_ashr_i32 s23, s10, 7
	s_and_b32 s43, s5, 0x7c
	s_add_i32 s5, s23, s26
	s_lshl_b32 s10, s35, 5
	s_lshl_b32 s5, s5, 6
	s_and_b32 s27, s10, 32
	s_or_b32 s10, s5, s27
	s_add_i32 s22, s22, 0x20100
	s_mul_i32 s11, s10, 0x3400
	s_mul_hi_i32 s5, s10, 0x3400
	s_add_u32 s38, s8, s11
	s_addc_u32 s5, s9, s5
	s_lshl_b32 s11, s4, 7
	s_lshl_b32 s42, s4, 8
	s_add_u32 s4, s38, s42
	s_addc_u32 s5, s5, 0
	v_lshlrev_b32_e32 v2, 1, v182
	v_lshl_add_u64 v[4:5], s[4:5], 0, v[2:3]
	v_mov_b32_e32 v149, v3
	v_lshl_add_u64 v[4:5], v[4:5], 0, v[148:149]
	s_mov_b64 s[4:5], 0x1c00
	v_sub_u32_e64 v12, 8, s43 clamp
	v_lshl_add_u64 v[6:7], v[4:5], 0, s[4:5]
	v_readfirstlane_b32 s4, v12
	s_add_i32 s45, s26, s4
	s_mul_i32 s46, s45, 0xd0000
	s_add_i32 s4, s45, -8
	s_add_i32 s5, s46, 0xff980000
	s_mul_hi_i32 s4, s4, 0xd0000
	s_add_u32 s5, s8, s5
	s_addc_u32 s4, s9, s4
	s_add_u32 s5, s5, s42
	s_addc_u32 s38, s4, 0
	s_add_u32 s4, s5, 0x2400
	s_addc_u32 s5, s38, 0
	s_lshl_b32 s47, s35, 3
	s_lshl_b32 s38, s35, 1
	v_add_co_u32_e32 v4, vcc, s33, v4
	v_or_b32_e32 v2, s47, v180
	s_and_b32 s38, s38, 2
	s_movk_i32 s49, 0x1a00
	v_addc_co_u32_e32 v5, vcc, 0, v5, vcc
	v_bitop3_b32 v13, s38, v177, v181 bitop3:0x36
	v_mad_i64_i32 v[132:133], s[38:39], v2, s49, 0
	s_load_dwordx2 s[40:41], s[0:1], 0xd0
	s_waitcnt lgkmcnt(0)
	s_waitcnt lgkmcnt(0)
	global_load_dwordx4 v[124:127], v[6:7], off offset:32
	global_load_dwordx4 v[120:123], v[6:7], off offset:64
	global_load_dwordx4 v[116:119], v[6:7], off offset:96
	global_load_dwordx4 v[112:115], v[6:7], off offset:128
	global_load_dwordx4 v[108:111], v[6:7], off offset:160
	global_load_dwordx4 v[104:107], v[6:7], off offset:192
	global_load_dwordx4 v[128:131], v[4:5], off offset:3072
	global_load_dwordx4 v[100:103], v[6:7], off offset:224
	v_lshlrev_b64 v[4:5], 1, v[132:133]
	s_lshl_b32 s35, s35, 11
	v_lshl_add_u64 v[6:7], s[4:5], 0, v[4:5]
	v_lshlrev_b32_e32 v2, 4, v13
	s_add_i32 s48, s35, 0
	v_lshl_add_u64 v[6:7], v[6:7], 0, v[2:3]
	s_mov_b32 m0, s48
	s_or_b32 s47, s47, 4
	global_load_lds_dwordx4 v[6:7], off
	v_lshl_add_u64 v[6:7], v[6:7], 0, s[36:37]
	s_add_i32 m0, s48, 0x4000
	s_bfe_u32 s38, s47, 0x20002
	global_load_lds_dwordx4 v[6:7], off
	v_or_b32_e32 v6, s47, v180
	v_bitop3_b32 v14, s38, v177, v181 bitop3:0x36
	v_mad_i64_i32 v[134:135], s[38:39], v6, s49, 0
	v_lshlrev_b64 v[6:7], 1, v[134:135]
	s_lshl_b32 s38, s47, 8
	v_lshl_add_u64 v[8:9], s[4:5], 0, v[6:7]
	v_lshlrev_b32_e32 v10, 4, v14
	v_mov_b32_e32 v11, v3
	s_add_i32 s39, s38, 0
	v_lshl_add_u64 v[8:9], v[8:9], 0, v[10:11]
	s_mov_b32 m0, s39
	s_add_i32 s4, s45, -7
	global_load_lds_dwordx4 v[8:9], off
	s_add_i32 m0, s39, 0x4000
	s_add_i32 s5, s46, 0xffa50000
	s_mul_hi_i32 s4, s4, 0xd0000
	s_add_u32 s5, s8, s5
	s_addc_u32 s4, s9, s4
	s_add_u32 s5, s5, s42
	s_addc_u32 s47, s4, 0
	s_add_u32 s4, s5, 0x2400
	v_lshl_add_u64 v[8:9], v[8:9], 0, s[36:37]
	s_addc_u32 s5, s47, 0
	global_load_lds_dwordx4 v[8:9], off
	v_lshl_add_u64 v[8:9], s[4:5], 0, v[4:5]
	v_lshl_add_u64 v[8:9], v[8:9], 0, v[2:3]
	s_add_i32 m0, s48, 0x8000
	s_add_i32 s45, s45, -6
	global_load_lds_dwordx4 v[8:9], off
	v_lshl_add_u64 v[8:9], v[8:9], 0, s[36:37]
	s_add_i32 m0, s48, 0xc000
	s_add_i32 s46, s46, 0xffb20000
	global_load_lds_dwordx4 v[8:9], off
	v_lshl_add_u64 v[8:9], s[4:5], 0, v[6:7]
	v_lshl_add_u64 v[8:9], v[8:9], 0, v[10:11]
	s_add_i32 m0, s39, 0x8000
	s_mul_hi_i32 s4, s45, 0xd0000
	global_load_lds_dwordx4 v[8:9], off
	s_add_i32 m0, s39, 0xc000
	s_add_u32 s5, s8, s46
	s_addc_u32 s4, s9, s4
	s_add_u32 s5, s5, s42
	s_addc_u32 s39, s4, 0
	s_add_u32 s4, s5, 0x2400
	s_addc_u32 s5, s39, 0
	v_lshl_add_u64 v[8:9], v[8:9], 0, s[36:37]
	v_lshl_add_u64 v[4:5], s[4:5], 0, v[4:5]
	global_load_lds_dwordx4 v[8:9], off
	v_lshl_add_u64 v[4:5], v[4:5], 0, v[2:3]
	s_add_i32 m0, s18, s35
	v_lshlrev_b32_e32 v20, 3, v14
	global_load_lds_dwordx4 v[4:5], off
	v_lshl_add_u64 v[4:5], v[4:5], 0, s[36:37]
	s_add_i32 m0, s19, s35
	v_mov_b32_e32 v18, v3
	global_load_lds_dwordx4 v[4:5], off
	v_lshl_add_u64 v[4:5], s[4:5], 0, v[6:7]
	v_lshl_add_u64 v[4:5], v[4:5], 0, v[10:11]
	s_add_i32 m0, s18, s38
	s_min_u32 s4, s43, 8
	global_load_lds_dwordx4 v[4:5], off
	v_lshl_add_u64 v[4:5], v[4:5], 0, s[36:37]
	s_add_i32 m0, s19, s38
	s_lshl_b32 s5, s4, 15
	global_load_lds_dwordx4 v[4:5], off
	s_lshl_b32 s45, s4, 6
	s_add_i32 s4, s23, s4
	s_lshl_b32 s4, s4, 6
	v_mov_b32_e32 v19, v3
	v_readfirstlane_b32 s42, v12
	v_lshlrev_b32_e32 v2, 3, v13
	s_or_b32 s4, s27, s4
	v_mov_b32_e32 v4, v3
	v_mov_b32_e32 v5, v3
	v_mov_b32_e32 v6, v3
	v_mov_b32_e32 v7, v3
	v_mov_b32_e32 v8, v3
	v_mov_b32_e32 v9, v3
	v_mov_b32_e32 v10, v3
	v_mov_b32_e32 v12, v3
	v_mov_b32_e32 v13, v3
	v_mov_b32_e32 v14, v3
	v_mov_b32_e32 v15, v3
	v_mov_b32_e32 v16, v3
	v_mov_b32_e32 v17, v3
	v_lshlrev_b32_e32 v136, 1, v20
	v_mov_b64_e32 v[34:35], v[18:19]
	v_mov_b64_e32 v[50:51], v[18:19]
	v_mov_b64_e32 v[66:67], v[18:19]
	s_mov_b32 s39, 0
	s_sub_i32 s43, 0x58000, s5
	v_add_u32_e32 v151, s4, v144
	s_sub_i32 s46, 0, s23
	v_mov_b32_e32 v145, 0
	v_mov_b32_e32 v149, 0xf149f2ca
	v_lshlrev_b32_e32 v2, 1, v2
	v_mov_b64_e32 v[32:33], v[16:17]
	v_mov_b64_e32 v[30:31], v[14:15]
	v_mov_b64_e32 v[28:29], v[12:13]
	v_mov_b64_e32 v[26:27], v[10:11]
	v_mov_b64_e32 v[24:25], v[8:9]
	v_mov_b64_e32 v[22:23], v[6:7]
	v_mov_b64_e32 v[20:21], v[4:5]
	v_mov_b64_e32 v[48:49], v[16:17]
	v_mov_b64_e32 v[46:47], v[14:15]
	v_mov_b64_e32 v[44:45], v[12:13]
	v_mov_b64_e32 v[42:43], v[10:11]
	v_mov_b64_e32 v[40:41], v[8:9]
	v_mov_b64_e32 v[38:39], v[6:7]
	v_mov_b64_e32 v[36:37], v[4:5]
	v_mov_b64_e32 v[64:65], v[16:17]
	v_mov_b64_e32 v[62:63], v[14:15]
	v_mov_b64_e32 v[60:61], v[12:13]
	v_mov_b64_e32 v[58:59], v[10:11]
	v_mov_b64_e32 v[56:57], v[8:9]
	v_mov_b64_e32 v[54:55], v[6:7]
	v_mov_b64_e32 v[52:53], v[4:5]
	s_waitcnt vmcnt(12)
	s_branch .LBB0_566

; #define LAS __attribute__((address_space(3)))
; #define WSP(T, off) ((T*)(kws() + (off)))
; template <int MODE, class Src>
; DI void attn_item(LAS unsigned char* lds, const Src& src, const bf16_t* Qp  , bf16_t* Op  , int nband, int jj0, float sink_l2, const LAS float* tbl, int qbase, int tid) {
;     ...
;     bf16x8 qf[8];
; #pragma unroll
;     for (int ks = 0; ks < 8; ++ks) qf[ks] = *(const bf16x8*)(Qp + (size_t)r * ZLD + ks * 16 + h * 8);
;     f32x16 o[4];
; #pragma unroll
;     for (int db = 0; db < 4; ++db)
; #pragma unroll
;         for (int i = 0; i < 16; ++i) o[db][i] = 0.f;
;     float mrun = MODE == 0 ? sink_l2 : -1e30f, lrun = MODE == 0 ? 1.f : 0.f;
;     const float sc = 0.08838834764831845f * LOG2E;
;     const LAS unsigned char* Kt = lds + hl * 16384 + 256 * r;
;     const int kx = 16 * (h ^ (((r & 3) << 2) | ((r >> 2) & 3)));
;     const int blk = (lane >> 4) & 1, q = (lane & 15) >> 2, p = lane & 3;
;     const LAS unsigned char* Vt = lds + 65536 + hl * 16384 + 256 * (4 * h + q) + 8 * (p & 1);
;     const int vlo = 2 * blk + (p >> 1);
;     ATT_ISSUE(jj0, false); ATT_ISSUE(jj0, true);
; __global__ void __launch_bounds__(NTHR, 2) fwd_kernel(Args args) {
;     ...
;                     for (int u = c.bid; u < 64; u += (nsmp ? nsmp : c.G)) {
;                         const int hg = u & 1, chunk = 256 + (u >> 1), head = hg * 4 + (c.wave >> 1), qh = c.wave & 1;
;                         const bf16_t* Z = WSP(bf16_t, WS_Z);
;                         SrcCb src{Z, WSP(bf16_t, WS_KCC), WSP(bf16_t, WS_VTCC), chunk, hg * 4};
;                         attn_item<1>(c.lds, src, Z + (size_t)(chunk * 64 + qh * 32) * ZLD + C_QC + head * 128, WSP(bf16_t, WS_BR) + (size_t)(chunk * 64 + qh * 32) * 3072 + 2048 + head * 128, 9, 0,
;                                      0.f, tbl + head * 260, qh * 32, c.tid);
.LBB0_662:
	s_mulk_i32 s60, 0x410
	s_add_i32 s12, s60, 0
	s_add_i32 s12, s12, 0x20100
	s_add_u32 s4, s4, s52
	v_mul_u32_u24_e32 v2, s8, v190
	s_addc_u32 s5, s5, s53
	v_lshlrev_b32_e32 v2, 1, v2
	v_lshl_add_u64 v[4:5], s[4:5], 0, v[2:3]
	v_mov_b32_e32 v159, v3
	s_add_i32 s95, s55, s54
	v_lshl_add_u64 v[4:5], v[4:5], 0, v[158:159]
	s_mov_b32 m0, s95
	s_mul_hi_u32 s4, s57, 0xd0000
	global_load_lds_dwordx4 v[4:5], off
	s_mul_i32 s57, s57, 0xd0000
	s_add_u32 s8, s58, s57
	s_addc_u32 s9, s59, s4
	s_add_u32 s4, s8, 0x2400
	s_addc_u32 s5, s9, 0
	s_add_u32 s8, s8, 0x2c00
	s_addc_u32 s9, s9, 0
	s_lshl_b32 s54, s56, 9
	v_add3_u32 v193, s55, v183, v179
	s_or_b32 s54, s54, 64
	s_mul_hi_i32 s55, s56, 0xd0000
	s_mul_i32 s56, s56, 0xd0000
	s_add_u32 s42, s42, s56
	s_addc_u32 s43, s43, s55
	v_mov_b32_e32 v16, v3
	v_mov_b32_e32 v17, v3
	s_add_u32 s56, s42, 0x32ea8c00
	v_mov_b32_e32 v2, v3
	v_mov_b32_e32 v4, v3
	v_mov_b32_e32 v5, v3
	v_mov_b32_e32 v6, v3
	v_mov_b32_e32 v7, v3
	v_mov_b32_e32 v8, v3
	v_mov_b32_e32 v9, v3
	v_mov_b32_e32 v10, v3
	v_mov_b32_e32 v11, v3
	v_mov_b32_e32 v12, v3
	v_mov_b32_e32 v13, v3
	v_mov_b32_e32 v14, v3
	v_mov_b32_e32 v15, v3
	v_mov_b64_e32 v[32:33], v[16:17]
	v_mov_b64_e32 v[48:49], v[16:17]
	v_mov_b64_e32 v[64:65], v[16:17]
	v_mov_b64_e32 v[80:81], v[16:17]
	v_add_u32_e32 v191, s61, v178
	s_addc_u32 s57, s43, 0
	s_mov_b32 s97, 0
	v_mov_b32_e32 v192, 0
	v_mov_b32_e32 v194, 0xf149f2ca
	v_mov_b64_e32 v[30:31], v[14:15]
	v_mov_b64_e32 v[28:29], v[12:13]
	v_mov_b64_e32 v[26:27], v[10:11]
	v_mov_b64_e32 v[24:25], v[8:9]
	v_mov_b64_e32 v[22:23], v[6:7]
	v_mov_b64_e32 v[20:21], v[4:5]
	v_mov_b64_e32 v[18:19], v[2:3]
	v_mov_b64_e32 v[46:47], v[14:15]
	v_mov_b64_e32 v[44:45], v[12:13]
	v_mov_b64_e32 v[42:43], v[10:11]
	v_mov_b64_e32 v[40:41], v[8:9]
	v_mov_b64_e32 v[38:39], v[6:7]
	v_mov_b64_e32 v[36:37], v[4:5]
	v_mov_b64_e32 v[34:35], v[2:3]
	v_mov_b64_e32 v[62:63], v[14:15]
	v_mov_b64_e32 v[60:61], v[12:13]
	v_mov_b64_e32 v[58:59], v[10:11]
	v_mov_b64_e32 v[56:57], v[8:9]
	v_mov_b64_e32 v[54:55], v[6:7]
	v_mov_b64_e32 v[52:53], v[4:5]
	v_mov_b64_e32 v[50:51], v[2:3]
	v_mov_b64_e32 v[78:79], v[14:15]
	v_mov_b64_e32 v[76:77], v[12:13]
	v_mov_b64_e32 v[74:75], v[10:11]
	v_mov_b64_e32 v[72:73], v[8:9]
	v_mov_b64_e32 v[70:71], v[6:7]
	v_mov_b64_e32 v[68:69], v[4:5]
	v_mov_b64_e32 v[66:67], v[2:3]
	s_mov_b32 s85, 0
	s_waitcnt vmcnt(16)
	s_branch .LBB0_665

; #define LAS __attribute__((address_space(3)))
; template <int I> DI const float* kin() { return (const float*)karg64<I * 8>(); }
; #define WSP(T, off) ((T*)(kws() + (off)))
; template <int MODE, class Src>
; DI void attn_item(LAS unsigned char* lds, const Src& src, const bf16_t* Qp  , bf16_t* Op  , int nband, int jj0, float sink_l2, const LAS float* tbl, int qbase, int tid) {
;     ...
;     bf16x8 qf[8];
; #pragma unroll
;     for (int ks = 0; ks < 8; ++ks) qf[ks] = *(const bf16x8*)(Qp + (size_t)r * ZLD + ks * 16 + h * 8);
;     f32x16 o[4];
; #pragma unroll
;     for (int db = 0; db < 4; ++db)
; #pragma unroll
;         for (int i = 0; i < 16; ++i) o[db][i] = 0.f;
;     float mrun = MODE == 0 ? sink_l2 : -1e30f, lrun = MODE == 0 ? 1.f : 0.f;
;     const float sc = 0.08838834764831845f * LOG2E;
;     const LAS unsigned char* Kt = lds + hl * 16384 + 256 * r;
;     const int kx = 16 * (h ^ (((r & 3) << 2) | ((r >> 2) & 3)));
;     const int blk = (lane >> 4) & 1, q = (lane & 15) >> 2, p = lane & 3;
;     const LAS unsigned char* Vt = lds + 65536 + hl * 16384 + 256 * (4 * h + q) + 8 * (p & 1);
;     const int vlo = 2 * blk + (p >> 1);
;     ATT_ISSUE(jj0, false); ATT_ISSUE(jj0, true);
; __global__ void __launch_bounds__(NTHR, 2) fwd_kernel(Args args) {
;     ...
;                     if (nsmp) {
;                         const int u = 512 + c.bid, chunk = u >> 1, kv = u & 1, head = kv * 4 + (c.wave >> 1), qh = c.wave & 1;
;                         const bf16_t* Z = WSP(bf16_t, WS_Z);
;                         SrcSwa src{Z, WSP(bf16_t, WS_KCB), WSP(bf16_t, WS_VTCB), chunk, kv};
;                         attn_item<0>(c.lds, src, Z + (size_t)(chunk * 64 + qh * 32) * ZLD + C_QB + head * 128, WSP(bf16_t, WS_BR) + (size_t)(chunk * 64 + qh * 32) * 3072 + 1024 + head * 128, 3, 0,
;                                      kin<17>()[l * 8 + head] * LOG2E, nullptr, 0, c.tid);
.LBB0_750:
	s_and_b64 vcc, exec, s[18:19]
	s_cbranch_vccz .LBB0_780
	v_readlane_b32 s4, v253, 59
	s_add_i32 s8, s10, s4
	v_readlane_b32 s4, v253, 60
	s_lshl_b32 s9, s70, 3
	s_or_b32 s10, s11, s4
	s_lshl_b32 s4, s8, 7
	s_add_i32 s22, s8, s9
	s_ashr_i32 s5, s4, 31
	s_ashr_i32 s23, s22, 31
	s_add_i32 s38, 0, 0x10000
	s_load_dwordx2 s[18:19], s[0:1], 0xd0
	s_waitcnt lgkmcnt(0)
	s_add_u32 s39, s18, 0x26456000
	s_addc_u32 s40, s19, 0
	s_load_dwordx2 s[8:9], s[0:1], 0xd0
	s_waitcnt lgkmcnt(0)
	s_add_u32 s41, s8, 0x38456000
	s_addc_u32 s42, s9, 0
	s_load_dwordx2 s[8:9], s[0:1], 0xd0
	s_waitcnt lgkmcnt(0)
	s_add_u32 s43, s8, 0x38656000
	s_mul_i32 s12, s10, 0x3400
	s_addc_u32 s50, s9, 0
	s_mul_hi_i32 s11, s10, 0x3400
	s_add_u32 s8, s39, s12
	s_addc_u32 s9, s40, s11
	s_lshl_b64 s[4:5], s[4:5], 1
	s_add_u32 s26, s8, s4
	s_addc_u32 s27, s9, s5
	s_lshl_b64 s[22:23], s[22:23], 2
	s_load_dwordx2 s[8:9], s[0:1], 0xd0
	s_waitcnt lgkmcnt(0)
	s_load_dwordx2 s[34:35], s[0:1], 0x88
	s_waitcnt lgkmcnt(0)
	s_add_u32 s22, s34, s22
	v_readfirstlane_b32 s11, v146
	s_addc_u32 s23, s35, s23
	s_ashr_i32 s11, s11, 3
	s_and_b32 s12, s11, -8
	s_lshr_b32 s11, s11, 2
	s_and_b32 s11, s11, 2
	v_readlane_b32 s56, v253, 63
	v_mov_b64_e32 v[4:5], s[22:23]
	v_lshlrev_b32_e32 v2, 1, v182
	v_bitop3_b32 v13, s11, v177, v181 bitop3:0x36
	v_readlane_b32 s57, v254, 0
	s_add_u32 s11, s41, s56
	global_load_dword v12, v[4:5], off
	v_lshl_add_u64 v[4:5], s[26:27], 0, v[2:3]
	s_addc_u32 s26, s42, s57
	v_readlane_b32 s22, v254, 1
	s_add_u32 s45, s39, s22
	v_readlane_b32 s22, v254, 58
	s_addc_u32 s51, s40, s22
	s_add_u32 s27, s45, 0x1800
	v_readlane_b32 s54, v254, 24
	s_addc_u32 s34, s51, 0
	v_readlane_b32 s55, v254, 25
	v_mov_b32_e32 v149, v3
	s_and_b64 s[22:23], s[54:55], exec
	v_lshl_add_u64 v[4:5], v[4:5], 0, v[148:149]
	s_cselect_b32 s23, s27, s11
	v_readlane_b32 s11, v254, 2
	v_lshl_add_u64 v[6:7], v[4:5], 0, s[28:29]
	v_add_co_u32_e32 v4, vcc, s33, v4
	s_cselect_b32 s22, s34, s26
	s_lshl_b32 s11, s11, 1
	v_addc_co_u32_e32 v5, vcc, 0, v5, vcc
	v_or_b32_e32 v152, s12, v180
	s_add_u32 s26, s23, s11
	v_readlane_b32 s34, v254, 26
	s_waitcnt lgkmcnt(0)
	global_load_dwordx4 v[114:117], v[6:7], off offset:32
	global_load_dwordx4 v[118:121], v[6:7], off offset:64
	global_load_dwordx4 v[122:125], v[6:7], off offset:96
	global_load_dwordx4 v[126:129], v[6:7], off offset:128
	global_load_dwordx4 v[130:133], v[6:7], off offset:160
	global_load_dwordx4 v[134:137], v[6:7], off offset:192
	global_load_dwordx4 v[138:141], v[4:5], off
	global_load_dwordx4 v[142:145], v[6:7], off offset:224
	s_addc_u32 s27, s22, 0
	v_mad_i64_i32 v[4:5], s[22:23], s34, v152, 0
	v_lshlrev_b64 v[4:5], 1, v[4:5]
	s_lshl_b32 s52, s12, 8
	v_lshl_add_u64 v[6:7], s[26:27], 0, v[4:5]
	v_lshlrev_b32_e32 v2, 4, v13
	s_add_i32 s22, s52, 0
	s_or_b32 s12, s12, 4
	v_lshl_add_u64 v[6:7], v[6:7], 0, v[2:3]
	s_mov_b32 m0, s22
	v_or_b32_e32 v154, s12, v180
	s_bfe_u32 s23, s12, 0x20002
	s_lshl_b32 s12, s12, 8
	global_load_lds_dwordx4 v[6:7], off
	v_bitop3_b32 v14, s23, v177, v181 bitop3:0x36
	v_mad_i64_i32 v[6:7], s[34:35], s34, v154, 0
	s_add_i32 s23, s12, 0
	s_add_u32 s34, s43, s56
	s_addc_u32 s35, s50, s57
	s_add_u32 s45, s45, 0x1a00
	v_lshlrev_b64 v[6:7], 1, v[6:7]
	s_addc_u32 s51, s51, 0
	v_lshl_add_u64 v[8:9], s[26:27], 0, v[6:7]
	s_and_b64 s[26:27], s[54:55], exec
	s_cselect_b32 s26, s45, s34
	s_cselect_b32 s27, s51, s35
	s_add_u32 s26, s26, s11
	v_lshlrev_b32_e32 v10, 4, v14
	v_mov_b32_e32 v11, v3
	s_addc_u32 s27, s27, 0
	v_lshl_add_u64 v[8:9], v[8:9], 0, v[10:11]
	s_mov_b32 m0, s23
	v_lshl_add_u64 v[4:5], s[26:27], 0, v[4:5]
	global_load_lds_dwordx4 v[8:9], off
	v_lshl_add_u64 v[4:5], v[4:5], 0, v[2:3]
	s_add_i32 m0, s38, s52
	v_lshl_add_u32 v1, v1, 10, s38
	global_load_lds_dwordx4 v[4:5], off
	v_lshl_add_u64 v[4:5], s[26:27], 0, v[6:7]
	v_lshl_add_u64 v[4:5], v[4:5], 0, v[10:11]
	s_add_i32 m0, s38, s12
	v_readlane_b32 s12, v252, 5
	global_load_lds_dwordx4 v[4:5], off
	s_add_u32 s12, s39, s12
	v_readlane_b32 s26, v254, 60
	s_addc_u32 s34, s40, s26
	s_add_u32 s26, s12, 0x1800
	s_addc_u32 s27, s34, 0
	v_readlane_b32 s38, v254, 3
	v_readlane_b32 s39, v254, 4
	s_add_u32 s45, s41, s38
	s_addc_u32 s52, s42, s39
	s_add_u32 s53, s12, 0x1a00
	s_addc_u32 s54, s34, 0
	v_lshlrev_b32_e32 v2, 6, v177
	s_add_u32 s55, s43, s38
	v_and_b32_e32 v2, 0x300, v2
	s_addc_u32 s56, s50, s39
	v_readlane_b32 s12, v252, 6
	v_mov_b32_e32 v16, v3
	v_mov_b32_e32 v17, v3
	v_add3_u32 v155, v1, v2, v179
	s_waitcnt vmcnt(4)
	v_mul_f32_e32 v157, 0x3fb8aa3b, v12
	v_lshlrev_b32_e32 v156, 3, v13
	v_lshlrev_b32_e32 v158, 3, v14
	s_add_u32 s57, s18, s12
	v_readlane_b32 s12, v254, 61
	v_mov_b32_e32 v2, v3
	v_mov_b32_e32 v4, v3
	v_mov_b32_e32 v5, v3
	v_mov_b32_e32 v6, v3
	v_mov_b32_e32 v7, v3
	v_mov_b32_e32 v8, v3
	v_mov_b32_e32 v9, v3
	v_mov_b32_e32 v10, v3
	v_mov_b32_e32 v12, v3
	v_mov_b32_e32 v13, v3
	v_mov_b32_e32 v14, v3
	v_mov_b32_e32 v15, v3
	v_mov_b64_e32 v[32:33], v[16:17]
	v_mov_b64_e32 v[48:49], v[16:17]
	v_mov_b64_e32 v[64:65], v[16:17]
	v_mov_b64_e32 v[80:81], v[16:17]
	v_add_u32_e32 v153, 0, v178
	v_ashrrev_i32_e32 v1, 31, v152
	v_ashrrev_i32_e32 v149, 31, v154
	s_addc_u32 s58, s19, s12
	v_mov_b32_e32 v151, 1.0
	s_mov_b64 s[18:19], 0
	v_mov_b64_e32 v[30:31], v[14:15]
	v_mov_b64_e32 v[28:29], v[12:13]
	v_mov_b64_e32 v[26:27], v[10:11]
	v_mov_b64_e32 v[24:25], v[8:9]
	v_mov_b64_e32 v[22:23], v[6:7]
	v_mov_b64_e32 v[20:21], v[4:5]
	v_mov_b64_e32 v[18:19], v[2:3]
	v_mov_b64_e32 v[46:47], v[14:15]
	v_mov_b64_e32 v[44:45], v[12:13]
	v_mov_b64_e32 v[42:43], v[10:11]
	v_mov_b64_e32 v[40:41], v[8:9]
	v_mov_b64_e32 v[38:39], v[6:7]
	v_mov_b64_e32 v[36:37], v[4:5]
	v_mov_b64_e32 v[34:35], v[2:3]
	v_mov_b64_e32 v[62:63], v[14:15]
	v_mov_b64_e32 v[60:61], v[12:13]
	v_mov_b64_e32 v[58:59], v[10:11]
	v_mov_b64_e32 v[56:57], v[8:9]
	v_mov_b64_e32 v[54:55], v[6:7]
	v_mov_b64_e32 v[52:53], v[4:5]
	v_mov_b64_e32 v[50:51], v[2:3]
	v_mov_b64_e32 v[78:79], v[14:15]
	v_mov_b64_e32 v[76:77], v[12:13]
	v_mov_b64_e32 v[74:75], v[10:11]
	v_mov_b64_e32 v[72:73], v[8:9]
	v_mov_b64_e32 v[70:71], v[6:7]
	v_mov_b64_e32 v[68:69], v[4:5]
	v_mov_b64_e32 v[66:67], v[2:3]
	s_branch .LBB0_754
